# norm phases + final norm: row blocks assigned so that workgroups with blockIdx&7 = x take the rows of batch x (the row panels the GEMMs give XCD x): X is read and H written on the XCD that produced /
# baseline (speedup 1.0000x reference)
; #define LAS __attribute__((address_space(3)))
; #define TID() ({ int t__; asm volatile("v_mbcnt_lo_u32_b32 %0, -1, 0\n\tv_mbcnt_hi_u32_b32 %0, -1, %0" : "=v"(t__)); (wave_u << 6) | t__; })
; #define LANE_GW() int t_ = TID(); asm volatile("" : "+v"(t_)); const int ln = t_ & 63, wv = __builtin_amdgcn_readfirstlane(t_ >> 6), gwv = blockIdx.x * NWAVES + wv; (void)wv
; __device__ __forceinline__ void phase_prologue(const P& p, LAS unsigned char* lds, int gw, int NGW, int lane, int wave) {
;     LAS float* scr = (LAS float*)(lds + wave * 16384);
;     unsigned char* ws = p.ws;
;     constexpr int IT_ADA = 16 * 192, IT_IN = 16 * 385, IT_BRA = 16 * 32, IT_BRB = 32 * 32, IT_OUT = 16 * 32, IT_UP = 16 * 128, IT_DOWN = 64 * 32;
;     constexpr int IT_L = IT_ADA + IT_IN + IT_BRA + IT_BRB + IT_OUT + IT_UP + IT_DOWN;
;     for (int it = gw; it < DEPTH * IT_L; it += 2 * NGW) {
;         TItem a, b2; titem_decode(a, p, ws, it, IT_L); const bool hb = it + NGW < DEPTH * IT_L; titem_decode(b2, p, ws, hb ? it + NGW : it, IT_L);
; __global__ __launch_bounds__(NTHREADS, 2) void k_mega(P p) {
;     ...
;     const int G = gridDim.x, NGW = G * NWAVES;
;     unsigned char* ws = p.ws;
;     ...
;     volatile LAS unsigned* MISC = (volatile LAS unsigned*)(lds + MISC_OFF);
;     if (TID() < 16) MISC[TID()] = 0u;
;     __syncthreads();
;     XcdBarrier bar = xcd_barrier_post((unsigned*)(ws + WS_CTL) + CW_BAR, MISC + 8, TID());
;     ...
;     for (int rep = 0; rep < REP_P; ++rep) {   LANE_GW(); phase_prologue(p, lds, gwv, NGW, ln, wv); }
.LBB0_5:
	s_or_b64 exec, exec, s[2:3]
	s_load_dwordx16 s[4:19], s[0:1], 0x0
	s_lshl_b32 s96, s90, 3
	s_lshl_b32 s41, s90, 4
	s_waitcnt lgkmcnt(0)
	v_writelane_b32 v253, s4, 15
	s_nop 1
	v_writelane_b32 v253, s5, 16
	v_writelane_b32 v253, s6, 17
	v_writelane_b32 v253, s7, 18
	v_writelane_b32 v253, s8, 19
	v_writelane_b32 v253, s9, 20
	v_writelane_b32 v253, s10, 21
	v_writelane_b32 v253, s11, 22
	v_writelane_b32 v253, s12, 23
	v_writelane_b32 v253, s13, 24
	v_writelane_b32 v253, s14, 25
	v_writelane_b32 v253, s15, 26
	v_writelane_b32 v253, s16, 27
	v_writelane_b32 v253, s17, 28
	v_writelane_b32 v253, s18, 29
	v_writelane_b32 v253, s19, 30
	s_load_dwordx16 s[56:71], s[0:1], 0x40
	s_load_dwordx16 s[4:19], s[0:1], 0x80
	v_mbcnt_lo_u32_b32 v0, -1, 0
	v_mbcnt_hi_u32_b32 v0, -1, v0
	s_lshl_b32 s1, s52, 3
	v_or_b32_e32 v0, s54, v0
	s_waitcnt lgkmcnt(0)
	v_writelane_b32 v253, s4, 31
	v_readfirstlane_b32 s0, v0
	s_ashr_i32 s0, s0, 6
	v_writelane_b32 v253, s5, 32
	v_writelane_b32 v253, s6, 33
	v_writelane_b32 v253, s7, 34
	v_writelane_b32 v253, s8, 35
	v_writelane_b32 v253, s9, 36
	v_writelane_b32 v253, s10, 37
	v_writelane_b32 v253, s11, 38
	v_writelane_b32 v253, s12, 39
	v_writelane_b32 v253, s13, 40
	v_writelane_b32 v253, s14, 41
	v_writelane_b32 v253, s15, 42
	v_writelane_b32 v253, s16, 43
	v_writelane_b32 v253, s17, 44
	v_writelane_b32 v253, s18, 45
	v_writelane_b32 v253, s19, 46
	s_add_i32 s33, s0, s1
	s_and_b32 s2, s52, 7
	s_lshl_b32 s2, s2, 8
	s_and_b32 s3, s52, 0xf8
	s_or_b32 s2, s2, s3
	s_cmpk_eq_i32 s90, 0x100
	s_cselect_b32 s2, s2, s1
	v_writelane_b32 v253, s2, 47
	s_cmp_lt_i32 s33, 0xf040
	v_and_b32_e32 v6, 63, v0
	s_cbranch_scc0 .LBB0_60
	v_readlane_b32 s2, v253, 8
	v_readlane_b32 s3, v253, 9
	s_add_u32 s38, s2, 0x5000000
	s_addc_u32 s39, s3, 0
	s_add_u32 s40, s2, 0x2000000
	v_lshlrev_b32_e32 v2, 3, v6
	s_addc_u32 s42, s3, 0
	s_lshl_b32 s0, s0, 14
	v_lshrrev_b32_e32 v8, 3, v6
	v_and_b32_e32 v14, 56, v2
	s_add_i32 s0, s0, 0
	v_and_b32_e32 v0, 31, v0
	v_mul_u32_u24_e32 v2, 0x84, v14
	v_lshlrev_b32_e32 v4, 2, v8
	v_lshrrev_b32_e32 v7, 5, v6
	v_lshl_add_u32 v3, v0, 2, s0
	v_add3_u32 v9, s0, v2, v4
	s_lshl_b32 s0, s33, 5
	v_mov_b32_e32 v1, 0
	v_mul_u32_u24_e32 v13, 0x84, v7
	s_add_i32 s43, s0, 0xfff97e00
	s_lshl_b32 s0, s33, 1
	v_lshlrev_b32_e32 v2, 2, v0
	v_or_b32_e32 v10, 8, v8
	v_or_b32_e32 v11, 16, v8
	v_or_b32_e32 v12, 24, v8
	s_lshl_b32 s44, s41, 5
	s_add_i32 s45, s0, 0xffff97e0
	s_lshl_b32 s46, s41, 1
	v_mov_b32_e32 v4, v2
	v_mov_b32_e32 v5, v1
	v_lshlrev_b32_e32 v0, 1, v14
	v_add_u32_e32 v13, v3, v13
	s_mov_b32 s47, s33
	s_branch .LBB0_8
